# transposer bf16 weight stores write-through (sc1): less dirty L2 at the P0 barrier
# baseline (speedup 1.0000x reference)
; #define GAS __attribute__((address_space(1)))
; #define LAS __attribute__((address_space(3)))
; __device__ __forceinline__ unsigned pk2(float lo, float hi) { return f2bf(lo) | (f2bf(hi) << 16); }
; __device__ __forceinline__ void transpose_item(const float* W, const float* g  , int K, int N, bf16* WT, LAS float* scr, int kb, int nb, int lane) {
;     ...
;     const int c = lane & 7;
; #pragma unroll
;     for (int j = 0; j < 4; ++j) { const int n = (lane >> 3) + 8 * j; const LAS float* s = scr + (8 * c) * 33 + n;
;         v4u o; o.x = pk2(s[0 * 33], s[1 * 33]); o.y = pk2(s[2 * 33], s[3 * 33]); o.z = pk2(s[4 * 33], s[5 * 33]); o.w = pk2(s[6 * 33], s[7 * 33]);
;         *(GAS v4u*)(WT + (size_t)(n0 + n) * K + k0 + 8 * c) = o; }
.Lwt_nog_b:
.Lwt_noissue:
	s_waitcnt lgkmcnt(0)
	ds_read2_b32 v[194:195], v107 offset0:0 offset1:33
	ds_read2_b32 v[196:197], v107 offset0:66 offset1:99
	ds_read2_b32 v[198:199], v107 offset0:132 offset1:165
	ds_read2_b32 v[200:201], v107 offset0:198 offset1:231
	ds_read2_b32 v[202:203], v107 offset0:8 offset1:41
	ds_read2_b32 v[204:205], v107 offset0:74 offset1:107
	ds_read2_b32 v[206:207], v107 offset0:140 offset1:173
	ds_read2_b32 v[208:209], v107 offset0:206 offset1:239
	ds_read2_b32 v[210:211], v107 offset0:16 offset1:49
	ds_read2_b32 v[212:213], v107 offset0:82 offset1:115
	ds_read2_b32 v[214:215], v107 offset0:148 offset1:181
	ds_read2_b32 v[216:217], v107 offset0:214 offset1:247
	ds_read2_b32 v[218:219], v107 offset0:24 offset1:57
	ds_read2_b32 v[220:221], v107 offset0:90 offset1:123
	ds_read2_b32 v[222:223], v107 offset0:156 offset1:189
	ds_read2_b32 v[224:225], v107 offset0:222 offset1:255
	s_waitcnt lgkmcnt(15)
	v_mul_f32_e32 v194, v186, v194
	v_mul_f32_e32 v195, v187, v195
	v_cvt_pk_bf16_f32 v226, v194, v195
	s_waitcnt lgkmcnt(14)
	v_mul_f32_e32 v196, v188, v196
	v_mul_f32_e32 v197, v189, v197
	v_cvt_pk_bf16_f32 v227, v196, v197
	s_waitcnt lgkmcnt(13)
	v_mul_f32_e32 v198, v190, v198
	v_mul_f32_e32 v199, v191, v199
	v_cvt_pk_bf16_f32 v228, v198, v199
	s_waitcnt lgkmcnt(12)
	v_mul_f32_e32 v200, v192, v200
	v_mul_f32_e32 v201, v193, v201
	v_cvt_pk_bf16_f32 v229, v200, v201
	global_store_dwordx4 v142, v[226:229], s[52:53] sc1
	s_waitcnt lgkmcnt(11)
	v_mul_f32_e32 v202, v186, v202
	v_mul_f32_e32 v203, v187, v203
	v_cvt_pk_bf16_f32 v230, v202, v203
	s_waitcnt lgkmcnt(10)
	v_mul_f32_e32 v204, v188, v204
	v_mul_f32_e32 v205, v189, v205
	v_cvt_pk_bf16_f32 v231, v204, v205
	s_waitcnt lgkmcnt(9)
	v_mul_f32_e32 v206, v190, v206
	v_mul_f32_e32 v207, v191, v207
	v_cvt_pk_bf16_f32 v232, v206, v207
	s_waitcnt lgkmcnt(8)
	v_mul_f32_e32 v208, v192, v208
	v_mul_f32_e32 v209, v193, v209
	v_cvt_pk_bf16_f32 v233, v208, v209
	global_store_dwordx4 v143, v[230:233], s[52:53] sc1
	s_waitcnt lgkmcnt(7)
	v_mul_f32_e32 v210, v186, v210
	v_mul_f32_e32 v211, v187, v211
	v_cvt_pk_bf16_f32 v234, v210, v211
	s_waitcnt lgkmcnt(6)
	v_mul_f32_e32 v212, v188, v212
	v_mul_f32_e32 v213, v189, v213
	v_cvt_pk_bf16_f32 v235, v212, v213
	s_waitcnt lgkmcnt(5)
	v_mul_f32_e32 v214, v190, v214
	v_mul_f32_e32 v215, v191, v215
	v_cvt_pk_bf16_f32 v236, v214, v215
	s_waitcnt lgkmcnt(4)
	v_mul_f32_e32 v216, v192, v216
	v_mul_f32_e32 v217, v193, v217
	v_cvt_pk_bf16_f32 v237, v216, v217
	global_store_dwordx4 v144, v[234:237], s[52:53] sc1
	s_waitcnt lgkmcnt(3)
	v_mul_f32_e32 v218, v186, v218
	v_mul_f32_e32 v219, v187, v219
	v_cvt_pk_bf16_f32 v238, v218, v219
	s_waitcnt lgkmcnt(2)
	v_mul_f32_e32 v220, v188, v220
	v_mul_f32_e32 v221, v189, v221
	v_cvt_pk_bf16_f32 v239, v220, v221
	s_waitcnt lgkmcnt(1)
	v_mul_f32_e32 v222, v190, v222
	v_mul_f32_e32 v223, v191, v223
	v_cvt_pk_bf16_f32 v240, v222, v223
	s_waitcnt lgkmcnt(0)
	v_mul_f32_e32 v224, v192, v224
	v_mul_f32_e32 v225, v193, v225
	v_cvt_pk_bf16_f32 v241, v224, v225
	global_store_dwordx4 v145, v[238:241], s[52:53] sc1
	s_cmp_lt_u32 s37, s24
	s_cbranch_scc0 .Lwt_next
	s_waitcnt vmcnt(4)
	s_branch .Lwt_loop
